# baseline (speedup 1.0000x reference)
; #define MFMA32(a, b, c) __builtin_amdgcn_mfma_f32_32x32x16_bf16((a), (b), (c), 0, 0, 0)
; DI void gemm_mainloop(const bf16_t* __restrict__ A, int lda, const bf16_t* __restrict__ B, int ldb, int K,
;                       f32x16 (&acc)[2][4], char* smem, const int tid) {
;     ...
;   for (int kt = 0; kt < nk; ++kt) {
;     asm volatile("s_waitcnt vmcnt(8) lgkmcnt(0)" ::: "memory");
;     __builtin_amdgcn_s_barrier();
;     dma_stage(A, lda, B, ldb, (kt + 3) * 32, smem + ((kt + 3) & 3) * STG, w, lane);
;     const char* st = smem + (kt & 3) * STG;
;     _Pragma("unroll") for (int ks = 0; ks < 2; ++ks) {
;       const int oo = ks ? o1 : o0;
;       bf16x8 a0 = *(const bf16x8*)(st + aoff + oo);
;       bf16x8 a1 = *(const bf16x8*)(st + aoff + 32 * 64 + oo);
;       bf16x8 b0 = *(const bf16x8*)(st + boff + oo);
;       bf16x8 b1 = *(const bf16x8*)(st + boff + 32 * 64 + oo);
;       bf16x8 b2 = *(const bf16x8*)(st + boff + 64 * 64 + oo);
;       bf16x8 b3 = *(const bf16x8*)(st + boff + 96 * 64 + oo);
;       acc[0][0] = MFMA32(a0, b0, acc[0][0]); acc[0][1] = MFMA32(a0, b1, acc[0][1]);
;       acc[0][2] = MFMA32(a0, b2, acc[0][2]); acc[0][3] = MFMA32(a0, b3, acc[0][3]);
;       acc[1][0] = MFMA32(a1, b0, acc[1][0]); acc[1][1] = MFMA32(a1, b1, acc[1][1]);
;       acc[1][2] = MFMA32(a1, b2, acc[1][2]); acc[1][3] = MFMA32(a1, b3, acc[1][3]);
;     }
;   }
;   asm volatile("s_waitcnt vmcnt(0)" ::: "memory");
;   __syncthreads();
.LBB0_869:
	s_add_i32 s7, s6, 0x18000
	s_and_b32 s7, s7, 0x18000
	v_add_u32_e32 v152, s7, v192
	v_add_u32_e32 v182, v152, v193
	v_lshl_add_u64 v[178:179], v[172:173], 0, s[4:5]
	v_readfirstlane_b32 s7, v182
	v_lshl_add_u64 v[180:181], v[178:179], 0, s[20:21]
	s_mov_b32 m0, s7
	v_add_u32_e32 v184, v152, v194
	s_waitcnt vmcnt(8) lgkmcnt(0)
	s_barrier
	global_load_lds_dwordx4 v[180:181], off
	v_lshl_add_u64 v[180:181], v[170:171], 0, s[4:5]
	v_readfirstlane_b32 s7, v184
	v_add_u32_e32 v186, v152, v195
	v_lshl_add_u64 v[182:183], v[180:181], 0, s[20:21]
	s_mov_b32 m0, s7
	v_lshl_add_u64 v[184:185], v[176:177], 0, s[4:5]
	v_readfirstlane_b32 s7, v186
	v_add_u32_e32 v152, v152, v196
	global_load_lds_dwordx4 v[182:183], off
	v_lshl_add_u64 v[182:183], v[184:185], 0, s[20:21]
	s_mov_b32 m0, s7
	v_readfirstlane_b32 s7, v152
	global_load_lds_dwordx4 v[182:183], off
	v_lshl_add_u64 v[182:183], v[174:175], 0, s[4:5]
	s_mov_b32 m0, s7
	s_and_b32 s7, s6, 0x10000
	v_lshl_add_u64 v[186:187], v[182:183], 0, s[20:21]
	s_add_i32 s8, s7, 0
	global_load_lds_dwordx4 v[186:187], off
	v_add_u32_e32 v152, s8, v190
	v_add_u32_e32 v186, s8, v191
	v_add_u32_e32 v187, v152, v197
	v_add_u32_e32 v232, v186, v197
	ds_read_b128 v[208:211], v187
	ds_read_b128 v[212:215], v187 offset:2048
	ds_read_b128 v[216:219], v232 offset:16384
	ds_read_b128 v[220:223], v232 offset:18432
	ds_read_b128 v[224:227], v232 offset:20480
	ds_read_b128 v[228:231], v232 offset:22528
	s_waitcnt lgkmcnt(0)
	v_mfma_f32_32x32x16_bf16 v[112:127], v[208:211], v[216:219], v[112:127]
	v_add_u32_e32 v152, v152, v205
	v_add_u32_e32 v186, v186, v205
	v_lshl_add_u64 v[178:179], v[178:179], 0, s[24:25]
	s_add_u32 s4, s4, 0x80
	s_addc_u32 s5, s5, 0
	s_add_i32 s6, s6, 0x10000
	s_cmpk_lg_i32 s4, 0x800
	v_mfma_f32_32x32x16_bf16 v[96:111], v[208:211], v[220:223], v[96:111]
	v_mfma_f32_32x32x16_bf16 v[48:63], v[208:211], v[224:227], v[48:63]
	v_mfma_f32_32x32x16_bf16 v[32:47], v[208:211], v[228:231], v[32:47]
	v_mfma_f32_32x32x16_bf16 v[80:95], v[212:215], v[216:219], v[80:95]
	v_mfma_f32_32x32x16_bf16 v[64:79], v[212:215], v[220:223], v[64:79]
	v_mfma_f32_32x32x16_bf16 v[16:31], v[212:215], v[224:227], v[16:31]
	v_mfma_f32_32x32x16_bf16 v[0:15], v[212:215], v[228:231], v[0:15]
	ds_read_b128 v[208:211], v152
	ds_read_b128 v[212:215], v152 offset:2048
	ds_read_b128 v[216:219], v186 offset:16384
	ds_read_b128 v[220:223], v186 offset:18432
	ds_read_b128 v[224:227], v186 offset:20480
	ds_read_b128 v[228:231], v186 offset:22528
	s_waitcnt vmcnt(8) lgkmcnt(0)
	s_barrier
	s_waitcnt lgkmcnt(0)
	v_mfma_f32_32x32x16_bf16 v[112:127], v[208:211], v[216:219], v[112:127]
	v_mfma_f32_32x32x16_bf16 v[96:111], v[208:211], v[220:223], v[96:111]
	v_mfma_f32_32x32x16_bf16 v[48:63], v[208:211], v[224:227], v[48:63]
	v_mfma_f32_32x32x16_bf16 v[32:47], v[208:211], v[228:231], v[32:47]
	v_add_u32_e32 v208, s7, v192
	v_add_u32_e32 v209, v208, v193
	s_nop 0
	v_readfirstlane_b32 s7, v209
	s_mov_b32 m0, s7
	s_nop 0
	global_load_lds_dwordx4 v[178:179], off
	v_lshl_add_u64 v[178:179], v[180:181], 0, s[24:25]
	v_add_u32_e32 v180, v208, v194
	v_mfma_f32_32x32x16_bf16 v[80:95], v[212:215], v[216:219], v[80:95]
	v_readfirstlane_b32 s7, v180
	v_add_u32_e32 v180, v208, v195
	s_mov_b32 m0, s7
	v_readfirstlane_b32 s7, v180
	v_add_u32_e32 v180, v208, v196
	global_load_lds_dwordx4 v[178:179], off
	v_lshl_add_u64 v[178:179], v[184:185], 0, s[24:25]
	s_mov_b32 m0, s7
	v_readfirstlane_b32 s7, v180
	global_load_lds_dwordx4 v[178:179], off
	v_lshl_add_u64 v[178:179], v[182:183], 0, s[24:25]
	s_mov_b32 m0, s7
	v_mfma_f32_32x32x16_bf16 v[64:79], v[212:215], v[220:223], v[64:79]
	global_load_lds_dwordx4 v[178:179], off
	v_mfma_f32_32x32x16_bf16 v[16:31], v[212:215], v[224:227], v[16:31]
	v_mfma_f32_32x32x16_bf16 v[0:15], v[212:215], v[228:231], v[0:15]
	ds_read_b128 v[178:181], v187 offset:32768
	ds_read_b128 v[182:185], v187 offset:34816
	ds_read_b128 v[208:211], v232 offset:49152
	ds_read_b128 v[212:215], v232 offset:51200
	ds_read_b128 v[216:219], v232 offset:53248
	ds_read_b128 v[220:223], v232 offset:55296
	s_waitcnt lgkmcnt(0)
	v_mfma_f32_32x32x16_bf16 v[112:127], v[178:181], v[208:211], v[112:127]
	v_mfma_f32_32x32x16_bf16 v[96:111], v[178:181], v[212:215], v[96:111]
	v_mfma_f32_32x32x16_bf16 v[48:63], v[178:181], v[216:219], v[48:63]
	v_mfma_f32_32x32x16_bf16 v[32:47], v[178:181], v[220:223], v[32:47]
	v_mfma_f32_32x32x16_bf16 v[80:95], v[182:185], v[208:211], v[80:95]
	v_mfma_f32_32x32x16_bf16 v[64:79], v[182:185], v[212:215], v[64:79]
	v_mfma_f32_32x32x16_bf16 v[16:31], v[182:185], v[216:219], v[16:31]
	v_mfma_f32_32x32x16_bf16 v[0:15], v[182:185], v[220:223], v[0:15]
	ds_read_b128 v[178:181], v152 offset:32768
	ds_read_b128 v[182:185], v152 offset:34816
	ds_read_b128 v[208:211], v186 offset:49152
	ds_read_b128 v[212:215], v186 offset:51200
	ds_read_b128 v[216:219], v186 offset:53248
	ds_read_b128 v[220:223], v186 offset:55296
	s_waitcnt lgkmcnt(0)
	v_mfma_f32_32x32x16_bf16 v[112:127], v[178:181], v[208:211], v[112:127]
	v_mfma_f32_32x32x16_bf16 v[96:111], v[178:181], v[212:215], v[96:111]
	v_mfma_f32_32x32x16_bf16 v[48:63], v[178:181], v[216:219], v[48:63]
	v_mfma_f32_32x32x16_bf16 v[32:47], v[178:181], v[220:223], v[32:47]
	v_mfma_f32_32x32x16_bf16 v[80:95], v[182:185], v[208:211], v[80:95]
	v_mfma_f32_32x32x16_bf16 v[64:79], v[182:185], v[212:215], v[64:79]
	v_mfma_f32_32x32x16_bf16 v[16:31], v[182:185], v[216:219], v[16:31]
	v_mfma_f32_32x32x16_bf16 v[0:15], v[182:185], v[220:223], v[0:15]
	s_cbranch_scc1 .LBB0_869
	v_readlane_b32 s80, v250, 10
	v_readlane_b32 s84, v250, 14
	v_readlane_b32 s85, v250, 15
	s_waitcnt vmcnt(0)
	s_waitcnt vmcnt(0)
	s_barrier
; DI int crow(int i, int h) { return (i & 3) + 8 * (i >> 2) + 4 * h; }
; DI void stage_block(const f32x16& a0, const f32x16& a1, float* sE, int r, int h) {
;   _Pragma("unroll") for (int i = 0; i < 16; ++i) {
;     sE[crow(i, h) * EST + r] = a0[i];
;     sE[crow(i, h) * EST + 32 + r] = a1[i];
;   }
; }
; DI void p4_tile(const Params& P, int l, int t, char* smem) {
;     ...
;       stage_block(acc[mi][2 * seg], acc[mi][2 * seg + 1], sE, r, h);
;       _Pragma("unroll") for (int ps = 0; ps < 4; ++ps) {
;         const int rr = ps * 8 + (lane >> 3);
;         const size_t off = (size_t)(m0 + wm * 64 + mi * 32 + rr) * 2048 + gc;
;         float v[8]; read8(sE + rr * EST + ch * 8, v);
;         float g[8]; unpack8(*(const u32x4*)(P.mb + off), g);
;         float p[8]; unpack8(*(const u32x4*)(P.merged + off), p);
;         _Pragma("unroll") for (int j = 0; j < 8; ++j) v[j] = p[j] + v[j] * g[j];
;         *(u32x4*)(P.merged + off) = pack8u(v);
	ds_write_b32 v188, v112
	ds_write_b32 v189, v96 offset:128
	ds_write_b32 v188, v113 offset:272
	ds_write_b32 v189, v97 offset:400
	ds_write_b32 v188, v114 offset:544
	ds_write_b32 v189, v98 offset:672
	ds_write_b32 v188, v115 offset:816
	ds_write_b32 v189, v99 offset:944
	ds_write_b32 v188, v116 offset:2176
	ds_write_b32 v189, v100 offset:2304
	ds_write_b32 v188, v117 offset:2448
	ds_write_b32 v189, v101 offset:2576
	ds_write_b32 v188, v118 offset:2720
	ds_write_b32 v189, v102 offset:2848
	ds_write_b32 v188, v119 offset:2992
	ds_write_b32 v189, v103 offset:3120
	ds_write_b32 v188, v120 offset:4352
	ds_write_b32 v189, v104 offset:4480
	ds_write_b32 v188, v121 offset:4624
	ds_write_b32 v189, v105 offset:4752
	ds_write_b32 v188, v122 offset:4896
	ds_write_b32 v189, v106 offset:5024
	ds_write_b32 v188, v123 offset:5168
	ds_write_b32 v189, v107 offset:5296
	ds_write_b32 v188, v124 offset:6528
	ds_write_b32 v189, v108 offset:6656
	ds_write_b32 v188, v125 offset:6800
	ds_write_b32 v189, v109 offset:6928
	ds_write_b32 v188, v126 offset:7072
	ds_write_b32 v189, v110 offset:7200
	ds_write_b32 v188, v127 offset:7344
	ds_write_b32 v189, v111 offset:7472
	v_lshl_add_u64 v[100:101], v[168:169], 1, s[84:85]
	global_load_dwordx4 v[96:99], v[100:101], off
	global_load_dwordx4 v[106:109], v[128:129], off
	v_add_u32_e32 v104, v206, v207
	ds_read_b128 v[110:113], v104
	ds_read_b128 v[114:117], v104 offset:16
	s_add_i32 s17, s17, s74
	s_add_i32 s16, s16, s23
	s_add_i32 s15, s15, s36
	s_cmpk_gt_i32 s17, 0x1ff
	v_readlane_b32 s81, v250, 11
	v_readlane_b32 s82, v250, 12
	v_readlane_b32 s83, v250, 13
	v_readlane_b32 s86, v250, 16
	v_readlane_b32 s87, v250, 17
	v_readlane_b32 s88, v250, 18
	v_readlane_b32 s89, v250, 19
	v_readlane_b32 s90, v250, 20
	v_readlane_b32 s91, v250, 21
	v_readlane_b32 s92, v250, 22
	v_readlane_b32 s93, v250, 23
	v_readlane_b32 s94, v250, 24
	v_readlane_b32 s95, v250, 25
	s_waitcnt vmcnt(1)
	v_lshlrev_b32_e32 v102, 16, v96
	v_and_b32_e32 v103, 0xffff0000, v96
	s_waitcnt vmcnt(0)
	v_lshlrev_b32_e32 v118, 16, v106
	v_and_b32_e32 v119, 0xffff0000, v106
	v_lshlrev_b32_e32 v96, 16, v97
	v_and_b32_e32 v97, 0xffff0000, v97
	v_lshlrev_b32_e32 v106, 16, v107
	v_and_b32_e32 v107, 0xffff0000, v107
	s_waitcnt lgkmcnt(1)
	v_pk_fma_f32 v[102:103], v[110:111], v[102:103], v[118:119]
	v_pk_fma_f32 v[106:107], v[112:113], v[96:97], v[106:107]
	v_lshlrev_b32_e32 v96, 16, v98
	v_and_b32_e32 v97, 0xffff0000, v98
	v_lshlrev_b32_e32 v110, 16, v108
	v_and_b32_e32 v111, 0xffff0000, v108
	s_waitcnt lgkmcnt(0)
	v_pk_fma_f32 v[110:111], v[114:115], v[96:97], v[110:111]
	v_lshlrev_b32_e32 v96, 16, v99
	v_and_b32_e32 v97, 0xffff0000, v99
	v_lshlrev_b32_e32 v98, 16, v109
	v_and_b32_e32 v99, 0xffff0000, v109
	v_pk_fma_f32 v[108:109], v[116:117], v[96:97], v[98:99]
	v_cvt_pk_bf16_f32 v96, v102, v103
	v_cvt_pk_bf16_f32 v97, v106, v107
	v_cvt_pk_bf16_f32 v98, v110, v111
	v_cvt_pk_bf16_f32 v99, v108, v109
	global_store_dwordx4 v[128:129], v[96:99], off
	s_nop 1
	v_lshl_add_u64 v[96:97], v[166:167], 1, s[84:85]
	global_load_dwordx4 v[106:109], v[96:97], off
	global_load_dwordx4 v[110:113], v[130:131], off
	ds_read_b128 v[114:117], v104 offset:2176
	s_waitcnt vmcnt(1)
	v_lshlrev_b32_e32 v98, 16, v106
	v_and_b32_e32 v99, 0xffff0000, v106
	s_waitcnt vmcnt(0)
	v_lshlrev_b32_e32 v102, 16, v110
	v_and_b32_e32 v103, 0xffff0000, v110
	s_waitcnt lgkmcnt(0)
	v_pk_fma_f32 v[98:99], v[114:115], v[98:99], v[102:103]
	v_lshlrev_b32_e32 v102, 16, v107
	v_and_b32_e32 v103, 0xffff0000, v107
	v_lshlrev_b32_e32 v106, 16, v111
	v_and_b32_e32 v107, 0xffff0000, v111
	v_pk_fma_f32 v[102:103], v[116:117], v[102:103], v[106:107]
	ds_read_b128 v[114:117], v104 offset:2192
	v_lshlrev_b32_e32 v106, 16, v108
	v_and_b32_e32 v107, 0xffff0000, v108
	v_lshlrev_b32_e32 v110, 16, v112
	v_and_b32_e32 v111, 0xffff0000, v112
	s_waitcnt lgkmcnt(0)
	v_pk_fma_f32 v[110:111], v[114:115], v[106:107], v[110:111]
	v_lshlrev_b32_e32 v106, 16, v109
	v_and_b32_e32 v107, 0xffff0000, v109
	v_lshlrev_b32_e32 v108, 16, v113
	v_and_b32_e32 v109, 0xffff0000, v113
	v_pk_fma_f32 v[112:113], v[116:117], v[106:107], v[108:109]
	v_cvt_pk_bf16_f32 v106, v98, v99
	v_cvt_pk_bf16_f32 v107, v102, v103
	v_cvt_pk_bf16_f32 v108, v110, v111
	v_cvt_pk_bf16_f32 v109, v112, v113
	global_store_dwordx4 v[130:131], v[106:109], off
	v_lshl_add_u64 v[98:99], v[164:165], 1, s[84:85]
	global_load_dwordx4 v[106:109], v[98:99], off
	global_load_dwordx4 v[110:113], v[132:133], off
	ds_read_b128 v[114:117], v104 offset:4352
	s_waitcnt vmcnt(1)
	v_lshlrev_b32_e32 v102, 16, v106
	v_and_b32_e32 v103, 0xffff0000, v106
	s_waitcnt vmcnt(0)
	v_lshlrev_b32_e32 v118, 16, v110
	v_and_b32_e32 v119, 0xffff0000, v110
	v_lshlrev_b32_e32 v106, 16, v107
	v_and_b32_e32 v107, 0xffff0000, v107
	v_lshlrev_b32_e32 v110, 16, v111
	v_and_b32_e32 v111, 0xffff0000, v111
	s_waitcnt lgkmcnt(0)
	v_pk_fma_f32 v[102:103], v[114:115], v[102:103], v[118:119]
	v_pk_fma_f32 v[110:111], v[116:117], v[106:107], v[110:111]
	ds_read_b128 v[114:117], v104 offset:4368
	v_lshlrev_b32_e32 v106, 16, v108
	v_and_b32_e32 v107, 0xffff0000, v108
	v_lshlrev_b32_e32 v118, 16, v112
	v_and_b32_e32 v119, 0xffff0000, v112
	s_waitcnt lgkmcnt(0)
	v_pk_fma_f32 v[114:115], v[114:115], v[106:107], v[118:119]
	v_lshlrev_b32_e32 v106, 16, v109
	v_and_b32_e32 v107, 0xffff0000, v109
	v_lshlrev_b32_e32 v108, 16, v113
	v_and_b32_e32 v109, 0xffff0000, v113
	v_pk_fma_f32 v[112:113], v[116:117], v[106:107], v[108:109]
	v_cvt_pk_bf16_f32 v106, v102, v103
	v_cvt_pk_bf16_f32 v107, v110, v111
	v_cvt_pk_bf16_f32 v108, v114, v115
	v_cvt_pk_bf16_f32 v109, v112, v113
	global_store_dwordx4 v[132:133], v[106:109], off
	v_lshl_add_u64 v[102:103], v[162:163], 1, s[84:85]
	global_load_dwordx4 v[106:109], v[102:103], off
	global_load_dwordx4 v[110:113], v[134:135], off
	ds_read_b128 v[114:117], v104 offset:6528
	ds_read_b128 v[118:121], v104 offset:6544
	s_waitcnt vmcnt(1)
; DI int crow(int i, int h) { return (i & 3) + 8 * (i >> 2) + 4 * h; }
; DI void stage_block(const f32x16& a0, const f32x16& a1, float* sE, int r, int h) {
;   _Pragma("unroll") for (int i = 0; i < 16; ++i) {
;     sE[crow(i, h) * EST + r] = a0[i];
;     sE[crow(i, h) * EST + 32 + r] = a1[i];
;   }
; }
; DI void p4_tile(const Params& P, int l, int t, char* smem) {
;     ...
;       stage_block(acc[mi][2 * seg], acc[mi][2 * seg + 1], sE, r, h);
;       _Pragma("unroll") for (int ps = 0; ps < 4; ++ps) {
;         const int rr = ps * 8 + (lane >> 3);
;         const size_t off = (size_t)(m0 + wm * 64 + mi * 32 + rr) * 2048 + gc;
;         float v[8]; read8(sE + rr * EST + ch * 8, v);
;         float g[8]; unpack8(*(const u32x4*)(P.mb + off), g);
;         float p[8]; unpack8(*(const u32x4*)(P.merged + off), p);
;         _Pragma("unroll") for (int j = 0; j < 8; ++j) v[j] = p[j] + v[j] * g[j];
;         *(u32x4*)(P.merged + off) = pack8u(v);
	v_lshlrev_b32_e32 v122, 16, v106
	v_and_b32_e32 v123, 0xffff0000, v106
	s_waitcnt vmcnt(0)
	v_lshlrev_b32_e32 v124, 16, v110
	v_and_b32_e32 v125, 0xffff0000, v110
	v_lshlrev_b32_e32 v106, 16, v107
	v_and_b32_e32 v107, 0xffff0000, v107
	v_lshlrev_b32_e32 v110, 16, v111
	v_and_b32_e32 v111, 0xffff0000, v111
	s_waitcnt lgkmcnt(1)
	v_pk_fma_f32 v[110:111], v[116:117], v[106:107], v[110:111]
	v_lshlrev_b32_e32 v106, 16, v108
	v_and_b32_e32 v107, 0xffff0000, v108
	v_lshlrev_b32_e32 v116, 16, v112
	v_and_b32_e32 v117, 0xffff0000, v112
	s_waitcnt lgkmcnt(0)
	v_pk_fma_f32 v[116:117], v[118:119], v[106:107], v[116:117]
	v_lshlrev_b32_e32 v106, 16, v109
	v_and_b32_e32 v107, 0xffff0000, v109
	v_lshlrev_b32_e32 v108, 16, v113
	v_and_b32_e32 v109, 0xffff0000, v113
	v_pk_fma_f32 v[114:115], v[114:115], v[122:123], v[124:125]
	v_pk_fma_f32 v[112:113], v[120:121], v[106:107], v[108:109]
	v_cvt_pk_bf16_f32 v106, v114, v115
	v_cvt_pk_bf16_f32 v107, v110, v111
	v_cvt_pk_bf16_f32 v108, v116, v117
	v_cvt_pk_bf16_f32 v109, v112, v113
	global_store_dwordx4 v[134:135], v[106:109], off
	ds_write_b32 v188, v80
	ds_write_b32 v189, v64 offset:128
	ds_write_b32 v188, v81 offset:272
	ds_write_b32 v189, v65 offset:400
	ds_write_b32 v188, v82 offset:544
	ds_write_b32 v189, v66 offset:672
	ds_write_b32 v188, v83 offset:816
	ds_write_b32 v189, v67 offset:944
	ds_write_b32 v188, v84 offset:2176
	ds_write_b32 v189, v68 offset:2304
	ds_write_b32 v188, v85 offset:2448
	ds_write_b32 v189, v69 offset:2576
	ds_write_b32 v188, v86 offset:2720
	ds_write_b32 v189, v70 offset:2848
	ds_write_b32 v188, v87 offset:2992
	ds_write_b32 v189, v71 offset:3120
	ds_write_b32 v188, v88 offset:4352
	ds_write_b32 v189, v72 offset:4480
	ds_write_b32 v188, v89 offset:4624
	ds_write_b32 v189, v73 offset:4752
	ds_write_b32 v188, v90 offset:4896
	ds_write_b32 v189, v74 offset:5024
	ds_write_b32 v188, v91 offset:5168
	ds_write_b32 v189, v75 offset:5296
	ds_write_b32 v188, v92 offset:6528
	ds_write_b32 v189, v76 offset:6656
	ds_write_b32 v188, v93 offset:6800
	ds_write_b32 v189, v77 offset:6928
	ds_write_b32 v188, v94 offset:7072
	ds_write_b32 v189, v78 offset:7200
	ds_write_b32 v188, v95 offset:7344
	ds_write_b32 v189, v79 offset:7472
	v_lshl_add_u64 v[64:65], v[158:159], 1, s[84:85]
	global_load_dwordx4 v[66:69], v[64:65], off
	global_load_dwordx4 v[70:73], v[136:137], off
	ds_read_b128 v[74:77], v104
	ds_read_b128 v[78:81], v104 offset:16
	s_waitcnt vmcnt(1)
	v_lshlrev_b32_e32 v82, 16, v66
	v_and_b32_e32 v83, 0xffff0000, v66
	s_waitcnt vmcnt(0)
	v_lshlrev_b32_e32 v84, 16, v70
	v_and_b32_e32 v85, 0xffff0000, v70
	v_lshlrev_b32_e32 v66, 16, v67
	v_and_b32_e32 v67, 0xffff0000, v67
	v_lshlrev_b32_e32 v70, 16, v71
	v_and_b32_e32 v71, 0xffff0000, v71
	s_waitcnt lgkmcnt(1)
	v_pk_fma_f32 v[70:71], v[76:77], v[66:67], v[70:71]
	v_lshlrev_b32_e32 v66, 16, v68
	v_and_b32_e32 v67, 0xffff0000, v68
	v_lshlrev_b32_e32 v76, 16, v72
	v_and_b32_e32 v77, 0xffff0000, v72
	s_waitcnt lgkmcnt(0)
	v_pk_fma_f32 v[76:77], v[78:79], v[66:67], v[76:77]
	v_lshlrev_b32_e32 v66, 16, v69
	v_and_b32_e32 v67, 0xffff0000, v69
	v_lshlrev_b32_e32 v68, 16, v73
	v_and_b32_e32 v69, 0xffff0000, v73
	v_pk_fma_f32 v[74:75], v[74:75], v[82:83], v[84:85]
	v_pk_fma_f32 v[72:73], v[80:81], v[66:67], v[68:69]
	v_cvt_pk_bf16_f32 v66, v74, v75
	v_cvt_pk_bf16_f32 v67, v70, v71
	v_cvt_pk_bf16_f32 v68, v76, v77
	v_cvt_pk_bf16_f32 v69, v72, v73
	global_store_dwordx4 v[136:137], v[66:69], off
	s_nop 1
	v_lshl_add_u64 v[66:67], v[160:161], 1, s[84:85]
	global_load_dwordx4 v[68:71], v[66:67], off
	global_load_dwordx4 v[72:75], v[138:139], off
	ds_read_b128 v[76:79], v104 offset:2176
	s_waitcnt vmcnt(1)
	v_lshlrev_b32_e32 v80, 16, v68
	v_and_b32_e32 v81, 0xffff0000, v68
	s_waitcnt vmcnt(0)
	v_lshlrev_b32_e32 v82, 16, v72
	v_and_b32_e32 v83, 0xffff0000, v72
	v_lshlrev_b32_e32 v68, 16, v69
	v_and_b32_e32 v69, 0xffff0000, v69
	v_lshlrev_b32_e32 v72, 16, v73
	v_and_b32_e32 v73, 0xffff0000, v73
	s_waitcnt lgkmcnt(0)
	v_pk_fma_f32 v[80:81], v[76:77], v[80:81], v[82:83]
	v_pk_fma_f32 v[72:73], v[78:79], v[68:69], v[72:73]
	ds_read_b128 v[76:79], v104 offset:2192
	v_lshlrev_b32_e32 v68, 16, v70
	v_and_b32_e32 v69, 0xffff0000, v70
	v_lshlrev_b32_e32 v82, 16, v74
	v_and_b32_e32 v83, 0xffff0000, v74
	s_waitcnt lgkmcnt(0)
	v_pk_fma_f32 v[76:77], v[76:77], v[68:69], v[82:83]
	v_lshlrev_b32_e32 v68, 16, v71
	v_and_b32_e32 v69, 0xffff0000, v71
	v_lshlrev_b32_e32 v70, 16, v75
	v_and_b32_e32 v71, 0xffff0000, v75
	v_pk_fma_f32 v[74:75], v[78:79], v[68:69], v[70:71]
	v_cvt_pk_bf16_f32 v68, v80, v81
	v_cvt_pk_bf16_f32 v69, v72, v73
	v_cvt_pk_bf16_f32 v70, v76, v77
	v_cvt_pk_bf16_f32 v71, v74, v75
	global_store_dwordx4 v[138:139], v[68:71], off
	s_nop 1
	v_lshl_add_u64 v[68:69], v[156:157], 1, s[84:85]
	global_load_dwordx4 v[70:73], v[68:69], off
	global_load_dwordx4 v[74:77], v[140:141], off
	ds_read_b128 v[78:81], v104 offset:4352
	s_waitcnt vmcnt(1)
	v_lshlrev_b32_e32 v82, 16, v70
	v_and_b32_e32 v83, 0xffff0000, v70
	s_waitcnt vmcnt(0)
	v_lshlrev_b32_e32 v84, 16, v74
	v_and_b32_e32 v85, 0xffff0000, v74
	v_lshlrev_b32_e32 v70, 16, v71
	v_and_b32_e32 v71, 0xffff0000, v71
	v_lshlrev_b32_e32 v74, 16, v75
	v_and_b32_e32 v75, 0xffff0000, v75
	s_waitcnt lgkmcnt(0)
	v_pk_fma_f32 v[82:83], v[78:79], v[82:83], v[84:85]
	v_pk_fma_f32 v[74:75], v[80:81], v[70:71], v[74:75]
	ds_read_b128 v[78:81], v104 offset:4368
	v_lshlrev_b32_e32 v70, 16, v72
	v_and_b32_e32 v71, 0xffff0000, v72
	v_lshlrev_b32_e32 v84, 16, v76
	v_and_b32_e32 v85, 0xffff0000, v76
	s_waitcnt lgkmcnt(0)
; DI void p4_tile(const Params& P, int l, int t, char* smem) {
;     ...
;   _Pragma("unroll") for (int seg = 0; seg < 2; ++seg) {
;     const int gc = n0 + wn * 128 + seg * 64 + ch * 8;
;     _Pragma("unroll") for (int mi = 0; mi < 2; ++mi) {
;       stage_block(acc[mi][2 * seg], acc[mi][2 * seg + 1], sE, r, h);
;       _Pragma("unroll") for (int ps = 0; ps < 4; ++ps) {
;         const int rr = ps * 8 + (lane >> 3);
;         const size_t off = (size_t)(m0 + wm * 64 + mi * 32 + rr) * 2048 + gc;
;         float v[8]; read8(sE + rr * EST + ch * 8, v);
;         float g[8]; unpack8(*(const u32x4*)(P.mb + off), g);
;         float p[8]; unpack8(*(const u32x4*)(P.merged + off), p);
;         _Pragma("unroll") for (int j = 0; j < 8; ++j) v[j] = p[j] + v[j] * g[j];
;         *(u32x4*)(P.merged + off) = pack8u(v);
	v_pk_fma_f32 v[78:79], v[78:79], v[70:71], v[84:85]
	v_lshlrev_b32_e32 v70, 16, v73
	v_and_b32_e32 v71, 0xffff0000, v73
	v_lshlrev_b32_e32 v72, 16, v77
	v_and_b32_e32 v73, 0xffff0000, v77
	v_pk_fma_f32 v[76:77], v[80:81], v[70:71], v[72:73]
	v_cvt_pk_bf16_f32 v70, v82, v83
	v_cvt_pk_bf16_f32 v71, v74, v75
	v_cvt_pk_bf16_f32 v72, v78, v79
	v_cvt_pk_bf16_f32 v73, v76, v77
	global_store_dwordx4 v[140:141], v[70:73], off
	s_nop 1
	v_lshl_add_u64 v[70:71], v[154:155], 1, s[84:85]
	global_load_dwordx4 v[72:75], v[70:71], off
	global_load_dwordx4 v[76:79], v[142:143], off
	ds_read_b128 v[80:83], v104 offset:6528
	ds_read_b128 v[84:87], v104 offset:6544
	s_waitcnt vmcnt(1)
	v_lshlrev_b32_e32 v88, 16, v72
	v_and_b32_e32 v89, 0xffff0000, v72
	s_waitcnt vmcnt(0)
	v_lshlrev_b32_e32 v90, 16, v76
	v_and_b32_e32 v91, 0xffff0000, v76
	v_lshlrev_b32_e32 v72, 16, v73
	v_and_b32_e32 v73, 0xffff0000, v73
	v_lshlrev_b32_e32 v76, 16, v77
	v_and_b32_e32 v77, 0xffff0000, v77
	s_waitcnt lgkmcnt(1)
	v_pk_fma_f32 v[76:77], v[82:83], v[72:73], v[76:77]
	v_lshlrev_b32_e32 v72, 16, v74
	v_and_b32_e32 v73, 0xffff0000, v74
	v_lshlrev_b32_e32 v82, 16, v78
	v_and_b32_e32 v83, 0xffff0000, v78
	s_waitcnt lgkmcnt(0)
	v_pk_fma_f32 v[82:83], v[84:85], v[72:73], v[82:83]
	v_lshlrev_b32_e32 v72, 16, v75
	v_and_b32_e32 v73, 0xffff0000, v75
	v_lshlrev_b32_e32 v74, 16, v79
	v_and_b32_e32 v75, 0xffff0000, v79
	v_pk_fma_f32 v[80:81], v[80:81], v[88:89], v[90:91]
	v_pk_fma_f32 v[78:79], v[86:87], v[72:73], v[74:75]
	v_cvt_pk_bf16_f32 v72, v80, v81
	v_cvt_pk_bf16_f32 v73, v76, v77
	v_cvt_pk_bf16_f32 v74, v82, v83
	v_cvt_pk_bf16_f32 v75, v78, v79
	global_store_dwordx4 v[142:143], v[72:75], off
	ds_write_b32 v188, v48
	ds_write_b32 v189, v32 offset:128
	ds_write_b32 v188, v49 offset:272
	ds_write_b32 v189, v33 offset:400
	ds_write_b32 v188, v50 offset:544
	ds_write_b32 v189, v34 offset:672
	ds_write_b32 v188, v51 offset:816
	ds_write_b32 v189, v35 offset:944
	ds_write_b32 v188, v52 offset:2176
	ds_write_b32 v189, v36 offset:2304
	ds_write_b32 v188, v53 offset:2448
	ds_write_b32 v189, v37 offset:2576
	ds_write_b32 v188, v54 offset:2720
	ds_write_b32 v189, v38 offset:2848
	ds_write_b32 v188, v55 offset:2992
	ds_write_b32 v189, v39 offset:3120
	ds_write_b32 v188, v56 offset:4352
	ds_write_b32 v189, v40 offset:4480
	ds_write_b32 v188, v57 offset:4624
	ds_write_b32 v189, v41 offset:4752
	ds_write_b32 v188, v58 offset:4896
	ds_write_b32 v189, v42 offset:5024
	ds_write_b32 v188, v59 offset:5168
	ds_write_b32 v189, v43 offset:5296
	ds_write_b32 v188, v60 offset:6528
	ds_write_b32 v189, v44 offset:6656
	ds_write_b32 v188, v61 offset:6800
	ds_write_b32 v189, v45 offset:6928
	ds_write_b32 v188, v62 offset:7072
	ds_write_b32 v189, v46 offset:7200
	ds_write_b32 v188, v63 offset:7344
	ds_write_b32 v189, v47 offset:7472
	global_load_dwordx4 v[208:211], v[100:101], off offset:128
	global_load_dwordx4 v[212:215], v[128:129], off offset:128
	global_load_dwordx4 v[216:219], v[96:97], off offset:128
	global_load_dwordx4 v[220:223], v[130:131], off offset:128
	global_load_dwordx4 v[224:227], v[98:99], off offset:128
	global_load_dwordx4 v[228:231], v[132:133], off offset:128
	global_load_dwordx4 v[232:235], v[102:103], off offset:128
	global_load_dwordx4 v[236:239], v[134:135], off offset:128
	ds_read_b128 v[40:43], v104
	ds_read_b128 v[44:47], v104 offset:16
	s_waitcnt vmcnt(7)
	v_lshlrev_b32_e32 v48, 16, v208
	v_and_b32_e32 v49, 0xffff0000, v208
	s_waitcnt vmcnt(6)
	v_lshlrev_b32_e32 v50, 16, v212
	v_and_b32_e32 v51, 0xffff0000, v212
	v_lshlrev_b32_e32 v32, 16, v209
	v_and_b32_e32 v33, 0xffff0000, v209
	v_lshlrev_b32_e32 v36, 16, v213
	v_and_b32_e32 v37, 0xffff0000, v213
	s_waitcnt lgkmcnt(1)
	v_pk_fma_f32 v[36:37], v[42:43], v[32:33], v[36:37]
	v_lshlrev_b32_e32 v32, 16, v210
	v_and_b32_e32 v33, 0xffff0000, v210
	v_lshlrev_b32_e32 v42, 16, v214
	v_and_b32_e32 v43, 0xffff0000, v214
	s_waitcnt lgkmcnt(0)
	v_pk_fma_f32 v[42:43], v[44:45], v[32:33], v[42:43]
	v_lshlrev_b32_e32 v32, 16, v211
	v_and_b32_e32 v33, 0xffff0000, v211
	v_lshlrev_b32_e32 v34, 16, v215
	v_and_b32_e32 v35, 0xffff0000, v215
	v_pk_fma_f32 v[40:41], v[40:41], v[48:49], v[50:51]
	v_pk_fma_f32 v[38:39], v[46:47], v[32:33], v[34:35]
	v_cvt_pk_bf16_f32 v32, v40, v41
	v_cvt_pk_bf16_f32 v33, v36, v37
	v_cvt_pk_bf16_f32 v34, v42, v43
	v_cvt_pk_bf16_f32 v35, v38, v39
	global_store_dwordx4 v[128:129], v[32:35], off offset:128
	global_load_dwordx4 v[208:211], v[64:65], off offset:128
	global_load_dwordx4 v[212:215], v[136:137], off offset:128
	s_nop 0
	ds_read_b128 v[40:43], v104 offset:2176
	s_waitcnt vmcnt(8)
	v_lshlrev_b32_e32 v44, 16, v216
	v_and_b32_e32 v45, 0xffff0000, v216
	s_waitcnt vmcnt(7)
	v_lshlrev_b32_e32 v46, 16, v220
	v_and_b32_e32 v47, 0xffff0000, v220
	v_lshlrev_b32_e32 v32, 16, v217
	v_and_b32_e32 v33, 0xffff0000, v217
	v_lshlrev_b32_e32 v36, 16, v221
	v_and_b32_e32 v37, 0xffff0000, v221
	s_waitcnt lgkmcnt(0)
	v_pk_fma_f32 v[44:45], v[40:41], v[44:45], v[46:47]
	v_pk_fma_f32 v[36:37], v[42:43], v[32:33], v[36:37]
	ds_read_b128 v[40:43], v104 offset:2192
	v_lshlrev_b32_e32 v32, 16, v218
	v_and_b32_e32 v33, 0xffff0000, v218
	v_lshlrev_b32_e32 v46, 16, v222
	v_and_b32_e32 v47, 0xffff0000, v222
	s_waitcnt lgkmcnt(0)
	v_pk_fma_f32 v[40:41], v[40:41], v[32:33], v[46:47]
	v_lshlrev_b32_e32 v32, 16, v219
	v_and_b32_e32 v33, 0xffff0000, v219
	v_lshlrev_b32_e32 v34, 16, v223
	v_and_b32_e32 v35, 0xffff0000, v223
	v_pk_fma_f32 v[38:39], v[42:43], v[32:33], v[34:35]
	v_cvt_pk_bf16_f32 v32, v44, v45
	v_cvt_pk_bf16_f32 v33, v36, v37
	v_cvt_pk_bf16_f32 v34, v40, v41
	v_cvt_pk_bf16_f32 v35, v38, v39
	global_store_dwordx4 v[130:131], v[32:35], off offset:128
	global_load_dwordx4 v[216:219], v[66:67], off offset:128
	global_load_dwordx4 v[220:223], v[138:139], off offset:128
	s_nop 0
	ds_read_b128 v[40:43], v104 offset:4352
	s_waitcnt vmcnt(9)
; DI void p4_tile(const Params& P, int l, int t, char* smem) {
;     ...
;   _Pragma("unroll") for (int seg = 0; seg < 2; ++seg) {
;     const int gc = n0 + wn * 128 + seg * 64 + ch * 8;
;     _Pragma("unroll") for (int mi = 0; mi < 2; ++mi) {
;       stage_block(acc[mi][2 * seg], acc[mi][2 * seg + 1], sE, r, h);
;       _Pragma("unroll") for (int ps = 0; ps < 4; ++ps) {
;         const int rr = ps * 8 + (lane >> 3);
;         const size_t off = (size_t)(m0 + wm * 64 + mi * 32 + rr) * 2048 + gc;
;         float v[8]; read8(sE + rr * EST + ch * 8, v);
;         float g[8]; unpack8(*(const u32x4*)(P.mb + off), g);
;         float p[8]; unpack8(*(const u32x4*)(P.merged + off), p);
;         _Pragma("unroll") for (int j = 0; j < 8; ++j) v[j] = p[j] + v[j] * g[j];
;         *(u32x4*)(P.merged + off) = pack8u(v);
	v_lshlrev_b32_e32 v44, 16, v224
	v_and_b32_e32 v45, 0xffff0000, v224
	s_waitcnt vmcnt(8)
	v_lshlrev_b32_e32 v46, 16, v228
	v_and_b32_e32 v47, 0xffff0000, v228
	v_lshlrev_b32_e32 v32, 16, v225
	v_and_b32_e32 v33, 0xffff0000, v225
	v_lshlrev_b32_e32 v36, 16, v229
	v_and_b32_e32 v37, 0xffff0000, v229
	s_waitcnt lgkmcnt(0)
	v_pk_fma_f32 v[44:45], v[40:41], v[44:45], v[46:47]
	v_pk_fma_f32 v[36:37], v[42:43], v[32:33], v[36:37]
	ds_read_b128 v[40:43], v104 offset:4368
	v_lshlrev_b32_e32 v32, 16, v226
	v_and_b32_e32 v33, 0xffff0000, v226
	v_lshlrev_b32_e32 v46, 16, v230
	v_and_b32_e32 v47, 0xffff0000, v230
	s_waitcnt lgkmcnt(0)
	v_pk_fma_f32 v[40:41], v[40:41], v[32:33], v[46:47]
	v_lshlrev_b32_e32 v32, 16, v227
	v_and_b32_e32 v33, 0xffff0000, v227
	v_lshlrev_b32_e32 v34, 16, v231
	v_and_b32_e32 v35, 0xffff0000, v231
	v_pk_fma_f32 v[38:39], v[42:43], v[32:33], v[34:35]
	v_cvt_pk_bf16_f32 v32, v44, v45
	v_cvt_pk_bf16_f32 v33, v36, v37
	v_cvt_pk_bf16_f32 v34, v40, v41
	v_cvt_pk_bf16_f32 v35, v38, v39
	global_store_dwordx4 v[132:133], v[32:35], off offset:128
	global_load_dwordx4 v[224:227], v[68:69], off offset:128
	global_load_dwordx4 v[228:231], v[140:141], off offset:128
	s_nop 0
	ds_read_b128 v[40:43], v104 offset:6528
	ds_read_b128 v[44:47], v104 offset:6544
	s_waitcnt vmcnt(10)
	v_lshlrev_b32_e32 v48, 16, v232
	v_and_b32_e32 v49, 0xffff0000, v232
	s_waitcnt vmcnt(9)
	v_lshlrev_b32_e32 v50, 16, v236
	v_and_b32_e32 v51, 0xffff0000, v236
	v_lshlrev_b32_e32 v32, 16, v233
	v_and_b32_e32 v33, 0xffff0000, v233
	v_lshlrev_b32_e32 v36, 16, v237
	v_and_b32_e32 v37, 0xffff0000, v237
	s_waitcnt lgkmcnt(1)
	v_pk_fma_f32 v[36:37], v[42:43], v[32:33], v[36:37]
	v_lshlrev_b32_e32 v32, 16, v234
	v_and_b32_e32 v33, 0xffff0000, v234
	v_lshlrev_b32_e32 v42, 16, v238
	v_and_b32_e32 v43, 0xffff0000, v238
	s_waitcnt lgkmcnt(0)
	v_pk_fma_f32 v[42:43], v[44:45], v[32:33], v[42:43]
	v_lshlrev_b32_e32 v32, 16, v235
	v_and_b32_e32 v33, 0xffff0000, v235
	v_lshlrev_b32_e32 v34, 16, v239
	v_and_b32_e32 v35, 0xffff0000, v239
	v_pk_fma_f32 v[40:41], v[40:41], v[48:49], v[50:51]
	v_pk_fma_f32 v[38:39], v[46:47], v[32:33], v[34:35]
	v_cvt_pk_bf16_f32 v32, v40, v41
	v_cvt_pk_bf16_f32 v33, v36, v37
	v_cvt_pk_bf16_f32 v34, v42, v43
	v_cvt_pk_bf16_f32 v35, v38, v39
	global_store_dwordx4 v[134:135], v[32:35], off offset:128
	ds_write_b32 v188, v16
	ds_write_b32 v189, v0 offset:128
	ds_write_b32 v188, v17 offset:272
	ds_write_b32 v189, v1 offset:400
	ds_write_b32 v188, v18 offset:544
	ds_write_b32 v189, v2 offset:672
	ds_write_b32 v188, v19 offset:816
	ds_write_b32 v189, v3 offset:944
	ds_write_b32 v188, v20 offset:2176
	ds_write_b32 v189, v4 offset:2304
	ds_write_b32 v188, v21 offset:2448
	ds_write_b32 v189, v5 offset:2576
	ds_write_b32 v188, v22 offset:2720
	ds_write_b32 v189, v6 offset:2848
	ds_write_b32 v188, v23 offset:2992
	ds_write_b32 v189, v7 offset:3120
	ds_write_b32 v188, v24 offset:4352
	ds_write_b32 v189, v8 offset:4480
	ds_write_b32 v188, v25 offset:4624
	ds_write_b32 v189, v9 offset:4752
	ds_write_b32 v188, v26 offset:4896
	ds_write_b32 v189, v10 offset:5024
	ds_write_b32 v188, v27 offset:5168
	ds_write_b32 v189, v11 offset:5296
	ds_write_b32 v188, v28 offset:6528
	ds_write_b32 v189, v12 offset:6656
	ds_write_b32 v188, v29 offset:6800
	ds_write_b32 v189, v13 offset:6928
	ds_write_b32 v188, v30 offset:7072
	ds_write_b32 v189, v14 offset:7200
	ds_write_b32 v188, v31 offset:7344
	ds_write_b32 v189, v15 offset:7472
	global_load_dwordx4 v[232:235], v[70:71], off offset:128
	global_load_dwordx4 v[236:239], v[142:143], off offset:128
	ds_read_b128 v[8:11], v104
	ds_read_b128 v[12:15], v104 offset:16
	s_waitcnt vmcnt(10)
	v_lshlrev_b32_e32 v16, 16, v208
	v_and_b32_e32 v17, 0xffff0000, v208
	s_waitcnt vmcnt(9)
	v_lshlrev_b32_e32 v18, 16, v212
	v_and_b32_e32 v19, 0xffff0000, v212
	v_lshlrev_b32_e32 v0, 16, v209
	v_and_b32_e32 v1, 0xffff0000, v209
	v_lshlrev_b32_e32 v4, 16, v213
	v_and_b32_e32 v5, 0xffff0000, v213
	s_waitcnt lgkmcnt(1)
; DI void p4_tile(const Params& P, int l, int t, char* smem) {
;     ...
;   _Pragma("unroll") for (int seg = 0; seg < 2; ++seg) {
;     const int gc = n0 + wn * 128 + seg * 64 + ch * 8;
;     _Pragma("unroll") for (int mi = 0; mi < 2; ++mi) {
;       stage_block(acc[mi][2 * seg], acc[mi][2 * seg + 1], sE, r, h);
;       _Pragma("unroll") for (int ps = 0; ps < 4; ++ps) {
;         const int rr = ps * 8 + (lane >> 3);
;         const size_t off = (size_t)(m0 + wm * 64 + mi * 32 + rr) * 2048 + gc;
;         float v[8]; read8(sE + rr * EST + ch * 8, v);
;         float g[8]; unpack8(*(const u32x4*)(P.mb + off), g);
;         float p[8]; unpack8(*(const u32x4*)(P.merged + off), p);
;         _Pragma("unroll") for (int j = 0; j < 8; ++j) v[j] = p[j] + v[j] * g[j];
;         *(u32x4*)(P.merged + off) = pack8u(v);
	v_pk_fma_f32 v[4:5], v[10:11], v[0:1], v[4:5]
	v_lshlrev_b32_e32 v0, 16, v210
	v_and_b32_e32 v1, 0xffff0000, v210
	v_lshlrev_b32_e32 v10, 16, v214
	v_and_b32_e32 v11, 0xffff0000, v214
	s_waitcnt lgkmcnt(0)
	v_pk_fma_f32 v[10:11], v[12:13], v[0:1], v[10:11]
	v_lshlrev_b32_e32 v0, 16, v211
	v_and_b32_e32 v1, 0xffff0000, v211
	v_lshlrev_b32_e32 v2, 16, v215
	v_and_b32_e32 v3, 0xffff0000, v215
	v_pk_fma_f32 v[8:9], v[8:9], v[16:17], v[18:19]
	v_pk_fma_f32 v[6:7], v[14:15], v[0:1], v[2:3]
	v_cvt_pk_bf16_f32 v0, v8, v9
	v_cvt_pk_bf16_f32 v1, v4, v5
	v_cvt_pk_bf16_f32 v2, v10, v11
	v_cvt_pk_bf16_f32 v3, v6, v7
	global_store_dwordx4 v[136:137], v[0:3], off offset:128
	s_nop 0
	ds_read_b128 v[8:11], v104 offset:2176
	s_waitcnt vmcnt(8)
	v_lshlrev_b32_e32 v12, 16, v216
	v_and_b32_e32 v13, 0xffff0000, v216
	s_waitcnt vmcnt(7)
	v_lshlrev_b32_e32 v14, 16, v220
	v_and_b32_e32 v15, 0xffff0000, v220
	v_lshlrev_b32_e32 v0, 16, v217
	v_and_b32_e32 v1, 0xffff0000, v217
	v_lshlrev_b32_e32 v4, 16, v221
	v_and_b32_e32 v5, 0xffff0000, v221
	s_waitcnt lgkmcnt(0)
	v_pk_fma_f32 v[12:13], v[8:9], v[12:13], v[14:15]
	v_pk_fma_f32 v[4:5], v[10:11], v[0:1], v[4:5]
	ds_read_b128 v[8:11], v104 offset:2192
	v_lshlrev_b32_e32 v0, 16, v218
	v_and_b32_e32 v1, 0xffff0000, v218
	v_lshlrev_b32_e32 v14, 16, v222
	v_and_b32_e32 v15, 0xffff0000, v222
	s_waitcnt lgkmcnt(0)
	v_pk_fma_f32 v[8:9], v[8:9], v[0:1], v[14:15]
	v_lshlrev_b32_e32 v0, 16, v219
	v_and_b32_e32 v1, 0xffff0000, v219
	v_lshlrev_b32_e32 v2, 16, v223
	v_and_b32_e32 v3, 0xffff0000, v223
	v_pk_fma_f32 v[6:7], v[10:11], v[0:1], v[2:3]
	v_cvt_pk_bf16_f32 v0, v12, v13
	v_cvt_pk_bf16_f32 v1, v4, v5
	v_cvt_pk_bf16_f32 v2, v8, v9
	v_cvt_pk_bf16_f32 v3, v6, v7
	global_store_dwordx4 v[138:139], v[0:3], off offset:128
	s_nop 0
	ds_read_b128 v[8:11], v104 offset:4352
	s_waitcnt vmcnt(6)
	v_lshlrev_b32_e32 v12, 16, v224
	v_and_b32_e32 v13, 0xffff0000, v224
	s_waitcnt vmcnt(5)
	v_lshlrev_b32_e32 v14, 16, v228
	v_and_b32_e32 v15, 0xffff0000, v228
	v_lshlrev_b32_e32 v0, 16, v225
	v_and_b32_e32 v1, 0xffff0000, v225
	v_lshlrev_b32_e32 v4, 16, v229
	v_and_b32_e32 v5, 0xffff0000, v229
	s_waitcnt lgkmcnt(0)
	v_pk_fma_f32 v[12:13], v[8:9], v[12:13], v[14:15]
	v_pk_fma_f32 v[4:5], v[10:11], v[0:1], v[4:5]
	ds_read_b128 v[8:11], v104 offset:4368
	v_lshlrev_b32_e32 v0, 16, v226
	v_and_b32_e32 v1, 0xffff0000, v226
	v_lshlrev_b32_e32 v14, 16, v230
	v_and_b32_e32 v15, 0xffff0000, v230
	s_waitcnt lgkmcnt(0)
	v_pk_fma_f32 v[8:9], v[8:9], v[0:1], v[14:15]
	v_lshlrev_b32_e32 v0, 16, v227
	v_and_b32_e32 v1, 0xffff0000, v227
	v_lshlrev_b32_e32 v2, 16, v231
	v_and_b32_e32 v3, 0xffff0000, v231
	v_pk_fma_f32 v[6:7], v[10:11], v[0:1], v[2:3]
	v_cvt_pk_bf16_f32 v0, v12, v13
	v_cvt_pk_bf16_f32 v1, v4, v5
	v_cvt_pk_bf16_f32 v2, v8, v9
	v_cvt_pk_bf16_f32 v3, v6, v7
	global_store_dwordx4 v[140:141], v[0:3], off offset:128
	s_nop 0
	ds_read_b128 v[8:11], v104 offset:6528
	ds_read_b128 v[12:15], v104 offset:6544
	s_waitcnt vmcnt(4)
	v_lshlrev_b32_e32 v16, 16, v232
	v_and_b32_e32 v17, 0xffff0000, v232
	s_waitcnt vmcnt(3)
	v_lshlrev_b32_e32 v18, 16, v236
	v_and_b32_e32 v19, 0xffff0000, v236
	v_lshlrev_b32_e32 v0, 16, v233
	v_and_b32_e32 v1, 0xffff0000, v233
	v_lshlrev_b32_e32 v4, 16, v237
	v_and_b32_e32 v5, 0xffff0000, v237
	s_waitcnt lgkmcnt(1)
	v_pk_fma_f32 v[4:5], v[10:11], v[0:1], v[4:5]
	v_lshlrev_b32_e32 v0, 16, v234
	v_and_b32_e32 v1, 0xffff0000, v234
	v_lshlrev_b32_e32 v10, 16, v238
	v_and_b32_e32 v11, 0xffff0000, v238
	s_waitcnt lgkmcnt(0)
	v_pk_fma_f32 v[10:11], v[12:13], v[0:1], v[10:11]
	v_lshlrev_b32_e32 v0, 16, v235
	v_and_b32_e32 v1, 0xffff0000, v235
	v_lshlrev_b32_e32 v2, 16, v239
	v_and_b32_e32 v3, 0xffff0000, v239
	v_pk_fma_f32 v[8:9], v[8:9], v[16:17], v[18:19]
	v_pk_fma_f32 v[6:7], v[14:15], v[0:1], v[2:3]
	v_cvt_pk_bf16_f32 v0, v8, v9
	v_cvt_pk_bf16_f32 v1, v4, v5
	v_cvt_pk_bf16_f32 v2, v10, v11
	v_cvt_pk_bf16_f32 v3, v6, v7
	global_store_dwordx4 v[142:143], v[0:3], off offset:128
	s_barrier
	s_cbranch_scc0 .LBB0_866
